# LRU pass-1: additionally prefetch six of the eight gate-weight fragments of the next channel tile during the current tile (copied into place at the loop top)
# baseline (speedup 1.0000x reference)
; __device__ __forceinline__ float bf2f(unsigned short b) { return __uint_as_float(((unsigned)b) << 16); }
; __device__ __forceinline__ unsigned cvt_pk_bf16(float lo, float hi) { unsigned r; asm volatile("v_cvt_pk_bf16_f32 %0, %1, %2" : "=v"(r) : "v"(lo), "v"(hi)); return r; }
; __device__ __forceinline__ int lru_pass1(const Params& P, int l, LAS unsigned char* lds, unsigned* qw) {
;     ...
;             const int c = h * 64 + lane; const float* cw = P.conv_w + l * 4 * 512 + c; const float w0 = cw[0], w1 = cw[512], w2 = cw[1024], w3 = cw[1536], cb = P.conv_b[l * 512 + c];
;             float xv[67];
; #pragma unroll
;             for (int i = 0; i < 67; ++i) { const int n = n0 - 2 + i; xv[i] = bf2f(xaS[i * 64 + lane]) * ((n >= 0 && n < Ls) ? 1.0f : 0.0f); }
; #pragma unroll
;             for (int p = 0; p < 64; p += 2) { const float xc0 = cb + w0 * xv[p] + w1 * xv[p + 1] + w2 * xv[p + 2] + w3 * xv[p + 3], xc1 = cb + w0 * xv[p + 1] + w1 * xv[p + 2] + w2 * xv[p + 3] + w3 * xv[p + 4];
;                 const unsigned pk = cvt_pk_bf16(xc0, xc1); xcS[p * 72 + lane] = (unsigned short)pk; xcS[(p + 1) * 72 + lane] = (unsigned short)(pk >> 16); }
.LBB0_555:
	s_or_b64 exec, exec, s[8:9]
	v_or_b32_e32 v4, v33, v184
	v_readlane_b32 s0, v254, 54
	v_lshlrev_b32_e32 v128, 2, v4
	v_readlane_b32 s1, v254, 55
	s_waitcnt lgkmcnt(0)
	s_nop 4
	global_load_dword v0, v128, s[0:1]
	global_load_dword v1, v128, s[0:1] offset:2048
	s_waitcnt vmcnt(2)
	v_lshl_add_u64 v[2:3], s[0:1], 0, v[128:129]
	v_add_co_u32_e32 v8, vcc, 0x1000, v2
	v_readlane_b32 s0, v254, 52
	s_nop 0
	v_addc_co_u32_e32 v9, vcc, 0, v3, vcc
	v_or_b32_e32 v128, s0, v4
	global_load_dword v3, v[8:9], off
	global_load_dword v2, v[8:9], off offset:2048
	v_lshl_add_u64 v[8:9], v[128:129], 2, s[52:53]
	global_load_dword v4, v[8:9], off
	ds_read_u16 v7, v186
	ds_read_u16 v8, v186 offset:128
	ds_read_u16 v9, v186 offset:256
	ds_read_u16 v10, v186 offset:384
	ds_read_u16 v11, v186 offset:512
	ds_read_u16 v13, v186 offset:640
	ds_read_u16 v15, v186 offset:768
	ds_read_u16 v17, v186 offset:896
	v_cmp_lt_u32_e32 vcc, v6, v5
	s_waitcnt lgkmcnt(7)
	v_lshlrev_b32_e32 v7, 16, v7
	v_add3_u32 v36, v36, v98, v37
	v_cndmask_b32_e64 v6, 0, 1.0, vcc
	v_mul_f32_e32 v16, v6, v7
	v_add_u32_e32 v6, -1, v37
	v_cmp_lt_u32_e32 vcc, v6, v5
	s_waitcnt lgkmcnt(6)
	v_lshlrev_b32_e32 v7, 16, v8
	s_movk_i32 s0, 0x44
	v_cndmask_b32_e64 v6, 0, 1.0, vcc
	v_cmp_lt_u32_e32 vcc, v37, v5
	v_mul_f32_e32 v14, v6, v7
	s_waitcnt lgkmcnt(5)
	v_lshlrev_b32_e32 v6, 16, v9
	v_cndmask_b32_e64 v7, 0, 1.0, vcc
	v_mul_f32_e32 v12, v7, v6
	v_or_b32_e32 v6, 1, v37
	v_cmp_lt_u32_e32 vcc, v6, v5
	s_waitcnt lgkmcnt(4)
	v_lshlrev_b32_e32 v7, 16, v10
	v_mul_lo_u32 v34, v34, s0
	v_cndmask_b32_e64 v6, 0, 1.0, vcc
	v_mul_f32_e32 v10, v6, v7
	v_or_b32_e32 v6, 2, v37
	v_cmp_lt_u32_e32 vcc, v6, v5
	s_waitcnt lgkmcnt(3)
	v_lshlrev_b32_e32 v7, 16, v11
	s_waitcnt lgkmcnt(0)
	v_lshlrev_b32_e32 v11, 16, v17
	v_cndmask_b32_e64 v6, 0, 1.0, vcc
	v_mul_f32_e32 v9, v6, v7
	v_or_b32_e32 v6, 3, v37
	v_cmp_lt_u32_e32 vcc, v6, v5
	v_lshlrev_b32_e32 v7, 16, v13
	s_mov_b64 s[0:1], 0x400
	v_cndmask_b32_e64 v6, 0, 1.0, vcc
	v_mul_f32_e32 v8, v6, v7
	v_or_b32_e32 v6, 4, v37
	v_cmp_lt_u32_e32 vcc, v6, v5
	v_lshlrev_b32_e32 v7, 16, v15
	ds_read_u16 v13, v186 offset:1024
	ds_read_u16 v15, v186 offset:1152
	ds_read_u16 v17, v186 offset:1280
	ds_read_u16 v18, v186 offset:1408
	ds_read_u16 v19, v186 offset:1536
	ds_read_u16 v21, v186 offset:1664
	ds_read_u16 v23, v186 offset:1792
	ds_read_u16 v25, v186 offset:1920
	v_cndmask_b32_e64 v6, 0, 1.0, vcc
	v_mul_f32_e32 v7, v6, v7
	v_or_b32_e32 v6, 5, v37
	v_cmp_lt_u32_e32 vcc, v6, v5
	s_waitcnt lgkmcnt(7)
	v_lshlrev_b32_e32 v13, 16, v13
	v_add_lshl_u32 v34, v34, v35, 1
	v_cndmask_b32_e64 v6, 0, 1.0, vcc
	v_mul_f32_e32 v6, v6, v11
	v_or_b32_e32 v11, 6, v37
	v_cmp_lt_u32_e32 vcc, v11, v5
	v_ashrrev_i32_e32 v35, 31, v34
	v_lshlrev_b64 v[102:103], 12, v[34:35]
	v_cndmask_b32_e64 v11, 0, 1.0, vcc
	v_mul_f32_e32 v24, v11, v13
	v_or_b32_e32 v11, 7, v37
	v_cmp_lt_u32_e32 vcc, v11, v5
	s_waitcnt lgkmcnt(6)
	v_lshlrev_b32_e32 v13, 16, v15
	v_and_b32_e32 v32, 7, v32
	v_cndmask_b32_e64 v11, 0, 1.0, vcc
	v_mul_f32_e32 v22, v11, v13
	v_or_b32_e32 v11, 8, v37
	v_cmp_lt_u32_e32 vcc, v11, v5
	s_waitcnt lgkmcnt(5)
	v_lshlrev_b32_e32 v13, 16, v17
	v_add_lshl_u32 v34, v208, v33, 2
	v_cndmask_b32_e64 v11, 0, 1.0, vcc
	v_mul_f32_e32 v20, v11, v13
	v_or_b32_e32 v11, 9, v37
	v_cmp_lt_u32_e32 vcc, v11, v5
	s_waitcnt lgkmcnt(4)
	v_lshlrev_b32_e32 v13, 16, v18
	v_mov_b32_e32 v35, v129
	v_cndmask_b32_e64 v11, 0, 1.0, vcc
	v_mul_f32_e32 v18, v11, v13
	v_or_b32_e32 v11, 10, v37
	v_cmp_lt_u32_e32 vcc, v11, v5
	s_waitcnt lgkmcnt(3)
	v_lshlrev_b32_e32 v13, 16, v19
	s_waitcnt lgkmcnt(0)
	v_lshlrev_b32_e32 v19, 16, v25
	v_cndmask_b32_e64 v11, 0, 1.0, vcc
	v_mul_f32_e32 v17, v11, v13
	v_or_b32_e32 v11, 11, v37
	v_cmp_lt_u32_e32 vcc, v11, v5
	v_lshlrev_b32_e32 v13, 16, v21
	s_waitcnt vmcnt(0)
	v_fma_f32 v16, v0, v16, v4
	v_cndmask_b32_e64 v11, 0, 1.0, vcc
	v_mul_f32_e32 v15, v11, v13
	v_or_b32_e32 v11, 12, v37
	v_cmp_lt_u32_e32 vcc, v11, v5
	v_lshlrev_b32_e32 v13, 16, v23
	ds_read_u16 v21, v186 offset:2048
	ds_read_u16 v23, v186 offset:2176
	ds_read_u16 v25, v186 offset:2304
	ds_read_u16 v26, v186 offset:2432
	ds_read_u16 v27, v186 offset:2560
	ds_read_u16 v29, v186 offset:2688
	ds_read_u16 v31, v186 offset:2816
	ds_read_u16 v39, v186 offset:2944
	v_cndmask_b32_e64 v11, 0, 1.0, vcc
	v_mul_f32_e32 v13, v11, v13
	v_or_b32_e32 v11, 13, v37
	v_cmp_lt_u32_e32 vcc, v11, v5
	s_waitcnt lgkmcnt(7)
	v_lshlrev_b32_e32 v21, 16, v21
	v_fmac_f32_e32 v16, v1, v14
	v_cndmask_b32_e64 v11, 0, 1.0, vcc
	v_mul_f32_e32 v11, v11, v19
	v_or_b32_e32 v19, 14, v37
	v_cmp_lt_u32_e32 vcc, v19, v5
	v_fma_f32 v14, v0, v14, v4
	v_fmac_f32_e32 v16, v3, v12
	v_cndmask_b32_e64 v19, 0, 1.0, vcc
	v_mul_f32_e32 v38, v19, v21
	v_or_b32_e32 v19, 15, v37
	v_cmp_lt_u32_e32 vcc, v19, v5
	s_waitcnt lgkmcnt(6)
	v_lshlrev_b32_e32 v21, 16, v23
	v_fmac_f32_e32 v14, v1, v12
	v_cndmask_b32_e64 v19, 0, 1.0, vcc
	v_mul_f32_e32 v30, v19, v21
	v_or_b32_e32 v19, 16, v37
	v_cmp_lt_u32_e32 vcc, v19, v5
	s_waitcnt lgkmcnt(5)
	v_lshlrev_b32_e32 v21, 16, v25
	v_fma_f32 v12, v0, v12, v4
	v_cndmask_b32_e64 v19, 0, 1.0, vcc
	v_mul_f32_e32 v28, v19, v21
	v_or_b32_e32 v19, 17, v37
	v_cmp_lt_u32_e32 vcc, v19, v5
	s_waitcnt lgkmcnt(4)
	v_lshlrev_b32_e32 v21, 16, v26
	v_fmac_f32_e32 v16, v2, v10
	v_cndmask_b32_e64 v19, 0, 1.0, vcc
	v_mul_f32_e32 v26, v19, v21
	v_or_b32_e32 v19, 18, v37
	v_cmp_lt_u32_e32 vcc, v19, v5
	s_waitcnt lgkmcnt(3)
	v_lshlrev_b32_e32 v21, 16, v27
	s_waitcnt lgkmcnt(0)
; __device__ __forceinline__ float bf2f(unsigned short b) { return __uint_as_float(((unsigned)b) << 16); }
; __device__ __forceinline__ unsigned cvt_pk_bf16(float lo, float hi) { unsigned r; asm volatile("v_cvt_pk_bf16_f32 %0, %1, %2" : "=v"(r) : "v"(lo), "v"(hi)); return r; }
; __device__ __forceinline__ int lru_pass1(const Params& P, int l, LAS unsigned char* lds, unsigned* qw) {
;     ...
;             for (int i = 0; i < 67; ++i) { const int n = n0 - 2 + i; xv[i] = bf2f(xaS[i * 64 + lane]) * ((n >= 0 && n < Ls) ? 1.0f : 0.0f); }
; #pragma unroll
;             for (int p = 0; p < 64; p += 2) { const float xc0 = cb + w0 * xv[p] + w1 * xv[p + 1] + w2 * xv[p + 2] + w3 * xv[p + 3], xc1 = cb + w0 * xv[p + 1] + w1 * xv[p + 2] + w2 * xv[p + 3] + w3 * xv[p + 4];
;                 const unsigned pk = cvt_pk_bf16(xc0, xc1); xcS[p * 72 + lane] = (unsigned short)pk; xcS[(p + 1) * 72 + lane] = (unsigned short)(pk >> 16); }
	v_lshlrev_b32_e32 v27, 16, v39
	v_cndmask_b32_e64 v19, 0, 1.0, vcc
	v_mul_f32_e32 v25, v19, v21
	v_or_b32_e32 v19, 19, v37
	v_cmp_lt_u32_e32 vcc, v19, v5
	v_lshlrev_b32_e32 v21, 16, v29
	v_fmac_f32_e32 v14, v3, v10
	v_cndmask_b32_e64 v19, 0, 1.0, vcc
	v_mul_f32_e32 v23, v19, v21
	v_or_b32_e32 v19, 20, v37
	v_cmp_lt_u32_e32 vcc, v19, v5
	v_lshlrev_b32_e32 v21, 16, v31
	ds_read_u16 v29, v186 offset:3072
	ds_read_u16 v31, v186 offset:3200
	ds_read_u16 v39, v186 offset:3328
	ds_read_u16 v40, v186 offset:3456
	ds_read_u16 v41, v186 offset:3584
	ds_read_u16 v43, v186 offset:3712
	ds_read_u16 v45, v186 offset:3840
	ds_read_u16 v47, v186 offset:3968
	v_cndmask_b32_e64 v19, 0, 1.0, vcc
	v_mul_f32_e32 v21, v19, v21
	v_or_b32_e32 v19, 21, v37
	v_cmp_lt_u32_e32 vcc, v19, v5
	s_waitcnt lgkmcnt(7)
	v_lshlrev_b32_e32 v29, 16, v29
	v_fmac_f32_e32 v12, v1, v10
	v_cndmask_b32_e64 v19, 0, 1.0, vcc
	v_mul_f32_e32 v19, v19, v27
	v_or_b32_e32 v27, 22, v37
	v_cmp_lt_u32_e32 vcc, v27, v5
	v_fma_f32 v10, v0, v10, v4
	v_fmac_f32_e32 v14, v2, v9
	v_cndmask_b32_e64 v27, 0, 1.0, vcc
	v_mul_f32_e32 v46, v27, v29
	v_or_b32_e32 v27, 23, v37
	v_cmp_lt_u32_e32 vcc, v27, v5
	s_waitcnt lgkmcnt(6)
	v_lshlrev_b32_e32 v29, 16, v31
	v_fmac_f32_e32 v12, v3, v9
	v_cndmask_b32_e64 v27, 0, 1.0, vcc
	v_mul_f32_e32 v44, v27, v29
	v_or_b32_e32 v27, 24, v37
	v_cmp_lt_u32_e32 vcc, v27, v5
	s_waitcnt lgkmcnt(5)
	v_lshlrev_b32_e32 v29, 16, v39
	v_fmac_f32_e32 v10, v1, v9
	v_cndmask_b32_e64 v27, 0, 1.0, vcc
	v_mul_f32_e32 v42, v27, v29
	v_or_b32_e32 v27, 25, v37
	v_cmp_lt_u32_e32 vcc, v27, v5
	s_waitcnt lgkmcnt(4)
	v_lshlrev_b32_e32 v29, 16, v40
	v_fma_f32 v9, v0, v9, v4
	v_cndmask_b32_e64 v27, 0, 1.0, vcc
	v_mul_f32_e32 v40, v27, v29
	v_or_b32_e32 v27, 26, v37
	v_cmp_lt_u32_e32 vcc, v27, v5
	s_waitcnt lgkmcnt(3)
	v_lshlrev_b32_e32 v29, 16, v41
	s_waitcnt lgkmcnt(0)
	v_lshlrev_b32_e32 v41, 16, v47
	v_cndmask_b32_e64 v27, 0, 1.0, vcc
	v_mul_f32_e32 v39, v27, v29
	v_or_b32_e32 v27, 27, v37
	v_cmp_lt_u32_e32 vcc, v27, v5
	v_lshlrev_b32_e32 v29, 16, v43
	v_fmac_f32_e32 v12, v2, v8
	v_cndmask_b32_e64 v27, 0, 1.0, vcc
	v_mul_f32_e32 v31, v27, v29
	v_or_b32_e32 v27, 28, v37
	v_cmp_lt_u32_e32 vcc, v27, v5
	v_lshlrev_b32_e32 v29, 16, v45
	ds_read_u16 v43, v186 offset:4096
	ds_read_u16 v45, v186 offset:4224
	ds_read_u16 v47, v186 offset:4352
	ds_read_u16 v48, v186 offset:4480
	ds_read_u16 v49, v186 offset:4608
	ds_read_u16 v51, v186 offset:4736
	ds_read_u16 v53, v186 offset:4864
	ds_read_u16 v55, v186 offset:4992
	v_cndmask_b32_e64 v27, 0, 1.0, vcc
	v_mul_f32_e32 v29, v27, v29
	v_or_b32_e32 v27, 29, v37
	v_cmp_lt_u32_e32 vcc, v27, v5
	s_waitcnt lgkmcnt(7)
	v_lshlrev_b32_e32 v43, 16, v43
	v_fmac_f32_e32 v10, v3, v8
	v_cndmask_b32_e64 v27, 0, 1.0, vcc
	v_mul_f32_e32 v27, v27, v41
	v_or_b32_e32 v41, 30, v37
	v_cmp_lt_u32_e32 vcc, v41, v5
	v_fmac_f32_e32 v9, v1, v8
	v_fma_f32 v8, v0, v8, v4
	v_cndmask_b32_e64 v41, 0, 1.0, vcc
	v_mul_f32_e32 v54, v41, v43
	v_or_b32_e32 v41, 31, v37
	v_cmp_lt_u32_e32 vcc, v41, v5
	s_waitcnt lgkmcnt(6)
	v_lshlrev_b32_e32 v43, 16, v45
	v_fmac_f32_e32 v10, v2, v7
	v_cndmask_b32_e64 v41, 0, 1.0, vcc
	v_mul_f32_e32 v52, v41, v43
	v_or_b32_e32 v41, 32, v37
	v_cmp_lt_u32_e32 vcc, v41, v5
	s_waitcnt lgkmcnt(5)
	v_lshlrev_b32_e32 v43, 16, v47
	v_fmac_f32_e32 v9, v3, v7
	v_cndmask_b32_e64 v41, 0, 1.0, vcc
	v_mul_f32_e32 v50, v41, v43
	v_or_b32_e32 v41, 33, v37
	v_cmp_lt_u32_e32 vcc, v41, v5
	s_waitcnt lgkmcnt(4)
	v_lshlrev_b32_e32 v43, 16, v48
	v_fmac_f32_e32 v8, v1, v7
	v_cndmask_b32_e64 v41, 0, 1.0, vcc
	v_mul_f32_e32 v48, v41, v43
	v_or_b32_e32 v41, 34, v37
	v_cmp_lt_u32_e32 vcc, v41, v5
	s_waitcnt lgkmcnt(3)
	v_lshlrev_b32_e32 v43, 16, v49
	s_waitcnt lgkmcnt(0)
	v_lshlrev_b32_e32 v49, 16, v55
	v_cndmask_b32_e64 v41, 0, 1.0, vcc
	v_mul_f32_e32 v47, v41, v43
	v_or_b32_e32 v41, 35, v37
	v_cmp_lt_u32_e32 vcc, v41, v5
	v_lshlrev_b32_e32 v43, 16, v51
	v_fma_f32 v7, v0, v7, v4
	v_cndmask_b32_e64 v41, 0, 1.0, vcc
	v_mul_f32_e32 v45, v41, v43
	v_or_b32_e32 v41, 36, v37
	v_cmp_lt_u32_e32 vcc, v41, v5
	v_lshlrev_b32_e32 v43, 16, v53
	ds_read_u16 v51, v186 offset:5120
	ds_read_u16 v53, v186 offset:5248
	ds_read_u16 v55, v186 offset:5376
	ds_read_u16 v56, v186 offset:5504
	ds_read_u16 v57, v186 offset:5632
	ds_read_u16 v59, v186 offset:5760
	ds_read_u16 v61, v186 offset:5888
	ds_read_u16 v63, v186 offset:6016
	v_cndmask_b32_e64 v41, 0, 1.0, vcc
	v_mul_f32_e32 v43, v41, v43
	v_or_b32_e32 v41, 37, v37
	v_cmp_lt_u32_e32 vcc, v41, v5
	s_waitcnt lgkmcnt(7)
	v_lshlrev_b32_e32 v51, 16, v51
	v_fmac_f32_e32 v9, v2, v6
	v_cndmask_b32_e64 v41, 0, 1.0, vcc
	v_mul_f32_e32 v41, v41, v49
	v_or_b32_e32 v49, 38, v37
	v_cmp_lt_u32_e32 vcc, v49, v5
	v_fmac_f32_e32 v8, v3, v6
	v_fmac_f32_e32 v7, v1, v6
	v_cndmask_b32_e64 v49, 0, 1.0, vcc
	v_mul_f32_e32 v62, v49, v51
	v_or_b32_e32 v49, 39, v37
	v_cmp_lt_u32_e32 vcc, v49, v5
	s_waitcnt lgkmcnt(6)
	v_lshlrev_b32_e32 v51, 16, v53
	v_fma_f32 v6, v0, v6, v4
	v_cndmask_b32_e64 v49, 0, 1.0, vcc
	v_mul_f32_e32 v60, v49, v51
	v_or_b32_e32 v49, 40, v37
	v_cmp_lt_u32_e32 vcc, v49, v5
	s_waitcnt lgkmcnt(5)
	v_lshlrev_b32_e32 v51, 16, v55
	v_fmac_f32_e32 v6, v1, v24
	v_cndmask_b32_e64 v49, 0, 1.0, vcc
	v_mul_f32_e32 v58, v49, v51
	v_or_b32_e32 v49, 41, v37
	v_cmp_lt_u32_e32 vcc, v49, v5
	s_waitcnt lgkmcnt(4)
	v_lshlrev_b32_e32 v51, 16, v56
	v_fmac_f32_e32 v8, v2, v24
	v_cndmask_b32_e64 v49, 0, 1.0, vcc
	v_mul_f32_e32 v56, v49, v51
	v_or_b32_e32 v49, 42, v37
	v_cmp_lt_u32_e32 vcc, v49, v5
	s_waitcnt lgkmcnt(3)
	v_lshlrev_b32_e32 v51, 16, v57
	s_waitcnt lgkmcnt(0)
; __device__ __forceinline__ float bf2f(unsigned short b) { return __uint_as_float(((unsigned)b) << 16); }
; __device__ __forceinline__ unsigned cvt_pk_bf16(float lo, float hi) { unsigned r; asm volatile("v_cvt_pk_bf16_f32 %0, %1, %2" : "=v"(r) : "v"(lo), "v"(hi)); return r; }
; __device__ __forceinline__ int lru_pass1(const Params& P, int l, LAS unsigned char* lds, unsigned* qw) {
;     ...
;             for (int i = 0; i < 67; ++i) { const int n = n0 - 2 + i; xv[i] = bf2f(xaS[i * 64 + lane]) * ((n >= 0 && n < Ls) ? 1.0f : 0.0f); }
; #pragma unroll
;             for (int p = 0; p < 64; p += 2) { const float xc0 = cb + w0 * xv[p] + w1 * xv[p + 1] + w2 * xv[p + 2] + w3 * xv[p + 3], xc1 = cb + w0 * xv[p + 1] + w1 * xv[p + 2] + w2 * xv[p + 3] + w3 * xv[p + 4];
;                 const unsigned pk = cvt_pk_bf16(xc0, xc1); xcS[p * 72 + lane] = (unsigned short)pk; xcS[(p + 1) * 72 + lane] = (unsigned short)(pk >> 16); }
	v_lshlrev_b32_e32 v57, 16, v63
	v_cndmask_b32_e64 v49, 0, 1.0, vcc
	v_mul_f32_e32 v55, v49, v51
	v_or_b32_e32 v49, 43, v37
	v_cmp_lt_u32_e32 vcc, v49, v5
	v_lshlrev_b32_e32 v51, 16, v59
	v_fmac_f32_e32 v6, v3, v22
	v_cndmask_b32_e64 v49, 0, 1.0, vcc
	v_mul_f32_e32 v53, v49, v51
	v_or_b32_e32 v49, 44, v37
	v_cmp_lt_u32_e32 vcc, v49, v5
	v_lshlrev_b32_e32 v51, 16, v61
	ds_read_u16 v59, v186 offset:6144
	ds_read_u16 v61, v186 offset:6272
	ds_read_u16 v63, v186 offset:6400
	ds_read_u16 v64, v186 offset:6528
	ds_read_u16 v66, v186 offset:6656
	ds_read_u16 v67, v186 offset:6784
	ds_read_u16 v69, v186 offset:6912
	ds_read_u16 v71, v186 offset:7040
	v_cndmask_b32_e64 v49, 0, 1.0, vcc
	v_mul_f32_e32 v51, v49, v51
	v_or_b32_e32 v49, 45, v37
	v_cmp_lt_u32_e32 vcc, v49, v5
	s_waitcnt lgkmcnt(7)
	v_lshlrev_b32_e32 v59, 16, v59
	v_fmac_f32_e32 v7, v3, v24
	v_cndmask_b32_e64 v49, 0, 1.0, vcc
	v_mul_f32_e32 v49, v49, v57
	v_or_b32_e32 v57, 46, v37
	v_cmp_lt_u32_e32 vcc, v57, v5
	v_fmac_f32_e32 v6, v2, v20
	v_fmac_f32_e32 v7, v2, v22
	v_cndmask_b32_e64 v57, 0, 1.0, vcc
	v_mul_f32_e32 v70, v57, v59
	v_or_b32_e32 v57, 47, v37
	v_cmp_lt_u32_e32 vcc, v57, v5
	s_waitcnt lgkmcnt(6)
	v_lshlrev_b32_e32 v59, 16, v61
	v_lshl_or_b32 v128, v32, 7, v206
	v_cndmask_b32_e64 v57, 0, 1.0, vcc
	v_mul_f32_e32 v68, v57, v59
	v_or_b32_e32 v57, 48, v37
	v_cmp_lt_u32_e32 vcc, v57, v5
	s_waitcnt lgkmcnt(5)
	v_lshlrev_b32_e32 v59, 16, v63
	s_mov_b64 s[50:51], 0
	v_cndmask_b32_e64 v57, 0, 1.0, vcc
	v_mul_f32_e32 v65, v57, v59
	v_or_b32_e32 v57, 49, v37
	v_cmp_lt_u32_e32 vcc, v57, v5
	s_waitcnt lgkmcnt(4)
	v_lshlrev_b32_e32 v59, 16, v64
	v_mov_b64_e32 v[156:157], v[128:129]
	v_cndmask_b32_e64 v57, 0, 1.0, vcc
	v_mul_f32_e32 v64, v57, v59
	v_or_b32_e32 v57, 50, v37
	v_cmp_lt_u32_e32 vcc, v57, v5
	s_waitcnt lgkmcnt(3)
	v_lshlrev_b32_e32 v59, 16, v66
	s_waitcnt lgkmcnt(0)
	v_lshlrev_b32_e32 v66, 16, v71
	v_cndmask_b32_e64 v57, 0, 1.0, vcc
	v_mul_f32_e32 v63, v57, v59
	v_or_b32_e32 v57, 51, v37
	v_cmp_lt_u32_e32 vcc, v57, v5
	v_lshlrev_b32_e32 v59, 16, v67
	v_mov_b32_e32 v213, v207
	v_cndmask_b32_e64 v57, 0, 1.0, vcc
	v_mul_f32_e32 v61, v57, v59
	v_or_b32_e32 v57, 52, v37
	v_cmp_lt_u32_e32 vcc, v57, v5
	v_lshlrev_b32_e32 v59, 16, v69
	ds_read_u16 v67, v186 offset:7168
	ds_read_u16 v69, v186 offset:7296
	ds_read_u16 v71, v186 offset:7424
	ds_read_u16 v72, v186 offset:7552
	ds_read_u16 v74, v186 offset:7680
	ds_read_u16 v75, v186 offset:7808
	ds_read_u16 v78, v186 offset:7936
	ds_read_u16 v79, v186 offset:8064
	v_cndmask_b32_e64 v57, 0, 1.0, vcc
	v_mul_f32_e32 v59, v57, v59
	v_or_b32_e32 v57, 53, v37
	v_cmp_lt_u32_e32 vcc, v57, v5
	s_waitcnt lgkmcnt(7)
	v_lshlrev_b32_e32 v67, 16, v67
	v_cndmask_b32_e64 v57, 0, 1.0, vcc
	v_mul_f32_e32 v57, v57, v66
	v_or_b32_e32 v66, 54, v37
	v_cmp_lt_u32_e32 vcc, v66, v5
	s_nop 1
	v_cndmask_b32_e64 v66, 0, 1.0, vcc
	v_mul_f32_e32 v77, v66, v67
	v_or_b32_e32 v66, 55, v37
	v_cmp_lt_u32_e32 vcc, v66, v5
	s_waitcnt lgkmcnt(6)
	v_lshlrev_b32_e32 v67, 16, v69
	v_cndmask_b32_e64 v66, 0, 1.0, vcc
	v_mul_f32_e32 v76, v66, v67
	v_or_b32_e32 v66, 56, v37
	v_cmp_lt_u32_e32 vcc, v66, v5
	s_waitcnt lgkmcnt(5)
	v_lshlrev_b32_e32 v67, 16, v71
	v_cndmask_b32_e64 v66, 0, 1.0, vcc
	v_mul_f32_e32 v73, v66, v67
	v_or_b32_e32 v66, 57, v37
	v_cmp_lt_u32_e32 vcc, v66, v5
	s_waitcnt lgkmcnt(4)
	v_lshlrev_b32_e32 v67, 16, v72
	v_cndmask_b32_e64 v66, 0, 1.0, vcc
	v_mul_f32_e32 v72, v66, v67
	v_or_b32_e32 v66, 58, v37
	v_cmp_lt_u32_e32 vcc, v66, v5
	s_waitcnt lgkmcnt(3)
	v_lshlrev_b32_e32 v67, 16, v74
	s_waitcnt lgkmcnt(0)
	v_lshlrev_b32_e32 v74, 16, v79
	v_cndmask_b32_e64 v66, 0, 1.0, vcc
	v_mul_f32_e32 v71, v66, v67
	v_or_b32_e32 v66, 59, v37
	v_cmp_lt_u32_e32 vcc, v66, v5
	v_lshlrev_b32_e32 v67, 16, v75
	ds_read_u16 v75, v186 offset:8192
	v_cndmask_b32_e64 v66, 0, 1.0, vcc
	v_mul_f32_e32 v69, v66, v67
	v_lshlrev_b32_e32 v67, 16, v78
	ds_read_u16 v78, v186 offset:8320
	ds_read_u16 v79, v186 offset:8448
	v_cvt_pk_bf16_f32 v14, v16, v14
	ds_write_b16 v187, v14
	ds_write_b16_d16_hi v187, v14 offset:144
	v_cvt_pk_bf16_f32 v10, v12, v10
	ds_write_b16 v187, v10 offset:288
	ds_write_b16_d16_hi v187, v10 offset:432
	v_cvt_pk_bf16_f32 v8, v9, v8
	ds_write_b16 v187, v8 offset:576
	ds_write_b16_d16_hi v187, v8 offset:720
	v_cvt_pk_bf16_f32 v6, v7, v6
	ds_write_b16 v187, v6 offset:864
	ds_write_b16_d16_hi v187, v6 offset:1008
	v_fma_f32 v6, v0, v24, v4
	v_fmac_f32_e32 v6, v1, v22
	v_fma_f32 v7, v0, v22, v4
	v_fmac_f32_e32 v6, v3, v20
	v_fmac_f32_e32 v7, v1, v20
	v_fmac_f32_e32 v6, v2, v18
	v_fmac_f32_e32 v7, v3, v18
	v_fmac_f32_e32 v7, v2, v17
	v_cvt_pk_bf16_f32 v6, v6, v7
	ds_write_b16 v187, v6 offset:1152
	ds_write_b16_d16_hi v187, v6 offset:1296
	v_fma_f32 v6, v0, v20, v4
	v_fmac_f32_e32 v6, v1, v18
	v_fma_f32 v7, v0, v18, v4
	v_fmac_f32_e32 v6, v3, v17
	v_fmac_f32_e32 v7, v1, v17
	v_fmac_f32_e32 v6, v2, v15
	v_fmac_f32_e32 v7, v3, v15
	v_fmac_f32_e32 v7, v2, v13
	v_cvt_pk_bf16_f32 v6, v6, v7
	ds_write_b16 v187, v6 offset:1440
	ds_write_b16_d16_hi v187, v6 offset:1584
	v_fma_f32 v6, v0, v17, v4
	v_fmac_f32_e32 v6, v1, v15
	v_fma_f32 v7, v0, v15, v4
	v_fmac_f32_e32 v6, v3, v13
	v_fmac_f32_e32 v7, v1, v13
	v_fmac_f32_e32 v6, v2, v11
	v_fmac_f32_e32 v7, v3, v11
	v_fmac_f32_e32 v7, v2, v38
	v_cvt_pk_bf16_f32 v6, v6, v7
	ds_write_b16 v187, v6 offset:1728
	ds_write_b16_d16_hi v187, v6 offset:1872
	v_fma_f32 v6, v0, v13, v4
	v_fmac_f32_e32 v6, v1, v11
	v_fma_f32 v7, v0, v11, v4
	v_fmac_f32_e32 v6, v3, v38
	v_fmac_f32_e32 v7, v1, v38
	v_fmac_f32_e32 v6, v2, v30
	v_fmac_f32_e32 v7, v3, v30
	v_fmac_f32_e32 v7, v2, v28
	v_cvt_pk_bf16_f32 v6, v6, v7
	ds_write_b16 v187, v6 offset:2016
; __device__ __forceinline__ unsigned cvt_pk_bf16(float lo, float hi) { unsigned r; asm volatile("v_cvt_pk_bf16_f32 %0, %1, %2" : "=v"(r) : "v"(lo), "v"(hi)); return r; }
; __device__ __forceinline__ int lru_pass1(const Params& P, int l, LAS unsigned char* lds, unsigned* qw) {
;     ...
;             for (int p = 0; p < 64; p += 2) { const float xc0 = cb + w0 * xv[p] + w1 * xv[p + 1] + w2 * xv[p + 2] + w3 * xv[p + 3], xc1 = cb + w0 * xv[p + 1] + w1 * xv[p + 2] + w2 * xv[p + 3] + w3 * xv[p + 4];
;                 const unsigned pk = cvt_pk_bf16(xc0, xc1); xcS[p * 72 + lane] = (unsigned short)pk; xcS[(p + 1) * 72 + lane] = (unsigned short)(pk >> 16); }
	ds_write_b16_d16_hi v187, v6 offset:2160
	v_fma_f32 v6, v0, v38, v4
	v_fmac_f32_e32 v6, v1, v30
	v_fma_f32 v7, v0, v30, v4
	v_fmac_f32_e32 v6, v3, v28
	v_fmac_f32_e32 v7, v1, v28
	v_fmac_f32_e32 v6, v2, v26
	v_fmac_f32_e32 v7, v3, v26
	v_fmac_f32_e32 v7, v2, v25
	v_cvt_pk_bf16_f32 v6, v6, v7
	ds_write_b16 v187, v6 offset:2304
	ds_write_b16_d16_hi v187, v6 offset:2448
	v_fma_f32 v6, v0, v28, v4
	v_fmac_f32_e32 v6, v1, v26
	v_fma_f32 v7, v0, v26, v4
	v_fmac_f32_e32 v6, v3, v25
	v_fmac_f32_e32 v7, v1, v25
	v_fmac_f32_e32 v6, v2, v23
	v_fmac_f32_e32 v7, v3, v23
	v_fmac_f32_e32 v7, v2, v21
	v_cvt_pk_bf16_f32 v6, v6, v7
	ds_write_b16 v187, v6 offset:2592
	ds_write_b16_d16_hi v187, v6 offset:2736
	v_fma_f32 v6, v0, v25, v4
	v_fmac_f32_e32 v6, v1, v23
	v_fma_f32 v7, v0, v23, v4
	v_fmac_f32_e32 v6, v3, v21
	v_fmac_f32_e32 v7, v1, v21
	v_fmac_f32_e32 v6, v2, v19
	v_fmac_f32_e32 v7, v3, v19
	v_fmac_f32_e32 v7, v2, v46
	v_cvt_pk_bf16_f32 v6, v6, v7
	ds_write_b16 v187, v6 offset:2880
	ds_write_b16_d16_hi v187, v6 offset:3024
	v_fma_f32 v6, v0, v21, v4
	v_fmac_f32_e32 v6, v1, v19
	v_fma_f32 v7, v0, v19, v4
	v_fmac_f32_e32 v6, v3, v46
	v_fmac_f32_e32 v7, v1, v46
	v_fmac_f32_e32 v6, v2, v44
	v_fmac_f32_e32 v7, v3, v44
	v_fmac_f32_e32 v7, v2, v42
	v_cvt_pk_bf16_f32 v6, v6, v7
	ds_write_b16 v187, v6 offset:3168
	ds_write_b16_d16_hi v187, v6 offset:3312
	v_fma_f32 v6, v0, v46, v4
	v_fmac_f32_e32 v6, v1, v44
	v_fma_f32 v7, v0, v44, v4
	v_fmac_f32_e32 v6, v3, v42
	v_fmac_f32_e32 v7, v1, v42
	v_fmac_f32_e32 v6, v2, v40
	v_fmac_f32_e32 v7, v3, v40
	v_fmac_f32_e32 v7, v2, v39
	v_cvt_pk_bf16_f32 v6, v6, v7
	ds_write_b16 v187, v6 offset:3456
	ds_write_b16_d16_hi v187, v6 offset:3600
	v_fma_f32 v6, v0, v42, v4
	v_fmac_f32_e32 v6, v1, v40
	v_fma_f32 v7, v0, v40, v4
	v_fmac_f32_e32 v6, v3, v39
	v_fmac_f32_e32 v7, v1, v39
	v_fmac_f32_e32 v6, v2, v31
	v_fmac_f32_e32 v7, v3, v31
	v_fmac_f32_e32 v7, v2, v29
	v_cvt_pk_bf16_f32 v6, v6, v7
	ds_write_b16 v187, v6 offset:3744
	ds_write_b16_d16_hi v187, v6 offset:3888
	v_fma_f32 v6, v0, v39, v4
	v_fmac_f32_e32 v6, v1, v31
	v_fma_f32 v7, v0, v31, v4
	v_fmac_f32_e32 v6, v3, v29
	v_fmac_f32_e32 v7, v1, v29
	v_fmac_f32_e32 v6, v2, v27
	v_fmac_f32_e32 v7, v3, v27
	v_fmac_f32_e32 v7, v2, v54
	v_cvt_pk_bf16_f32 v6, v6, v7
	ds_write_b16 v187, v6 offset:4032
	ds_write_b16_d16_hi v187, v6 offset:4176
	v_fma_f32 v6, v0, v29, v4
	v_fmac_f32_e32 v6, v1, v27
	v_fma_f32 v7, v0, v27, v4
	v_fmac_f32_e32 v6, v3, v54
	v_fmac_f32_e32 v7, v1, v54
	v_fmac_f32_e32 v6, v2, v52
	v_fmac_f32_e32 v7, v3, v52
	v_fmac_f32_e32 v7, v2, v50
	v_cvt_pk_bf16_f32 v6, v6, v7
	ds_write_b16 v187, v6 offset:4320
	ds_write_b16_d16_hi v187, v6 offset:4464
	v_fma_f32 v6, v0, v54, v4
	v_fmac_f32_e32 v6, v1, v52
	v_fma_f32 v7, v0, v52, v4
	v_fmac_f32_e32 v6, v3, v50
	v_fmac_f32_e32 v7, v1, v50
	v_fmac_f32_e32 v6, v2, v48
	v_fmac_f32_e32 v7, v3, v48
	v_fmac_f32_e32 v7, v2, v47
	v_cvt_pk_bf16_f32 v6, v6, v7
	ds_write_b16 v187, v6 offset:4608
	ds_write_b16_d16_hi v187, v6 offset:4752
	v_fma_f32 v6, v0, v50, v4
	v_fmac_f32_e32 v6, v1, v48
	v_fma_f32 v7, v0, v48, v4
	v_fmac_f32_e32 v6, v3, v47
	v_fmac_f32_e32 v7, v1, v47
	v_fmac_f32_e32 v6, v2, v45
	v_fmac_f32_e32 v7, v3, v45
	v_fmac_f32_e32 v7, v2, v43
	v_cvt_pk_bf16_f32 v6, v6, v7
	ds_write_b16 v187, v6 offset:4896
	ds_write_b16_d16_hi v187, v6 offset:5040
	v_fma_f32 v6, v0, v47, v4
	v_fmac_f32_e32 v6, v1, v45
	v_fma_f32 v7, v0, v45, v4
	v_fmac_f32_e32 v6, v3, v43
	v_fmac_f32_e32 v7, v1, v43
	v_fmac_f32_e32 v6, v2, v41
	v_fmac_f32_e32 v7, v3, v41
	v_fmac_f32_e32 v7, v2, v62
	v_cvt_pk_bf16_f32 v6, v6, v7
	ds_write_b16 v187, v6 offset:5184
	ds_write_b16_d16_hi v187, v6 offset:5328
	v_fma_f32 v6, v0, v43, v4
	v_fmac_f32_e32 v6, v1, v41
	v_fma_f32 v7, v0, v41, v4
	v_fmac_f32_e32 v6, v3, v62
	v_fmac_f32_e32 v7, v1, v62
	v_fmac_f32_e32 v6, v2, v60
	v_fmac_f32_e32 v7, v3, v60
	v_fmac_f32_e32 v7, v2, v58
	v_cvt_pk_bf16_f32 v6, v6, v7
	ds_write_b16 v187, v6 offset:5472
	ds_write_b16_d16_hi v187, v6 offset:5616
	v_fma_f32 v6, v0, v62, v4
	v_fmac_f32_e32 v6, v1, v60
	v_fma_f32 v7, v0, v60, v4
	v_fmac_f32_e32 v6, v3, v58
	v_fmac_f32_e32 v7, v1, v58
	v_fmac_f32_e32 v6, v2, v56
	v_fmac_f32_e32 v7, v3, v56
	v_fmac_f32_e32 v7, v2, v55
	v_cvt_pk_bf16_f32 v6, v6, v7
	ds_write_b16 v187, v6 offset:5760
	ds_write_b16_d16_hi v187, v6 offset:5904
	v_fma_f32 v6, v0, v58, v4
	v_fmac_f32_e32 v6, v1, v56
	v_fma_f32 v7, v0, v56, v4
	v_fmac_f32_e32 v6, v3, v55
	v_fmac_f32_e32 v7, v1, v55
	v_fmac_f32_e32 v6, v2, v53
	v_fmac_f32_e32 v7, v3, v53
	v_fmac_f32_e32 v7, v2, v51
	v_cvt_pk_bf16_f32 v6, v6, v7
	ds_write_b16 v187, v6 offset:6048
	ds_write_b16_d16_hi v187, v6 offset:6192
	v_fma_f32 v6, v0, v55, v4
	v_fmac_f32_e32 v6, v1, v53
	v_fma_f32 v7, v0, v53, v4
	v_fmac_f32_e32 v6, v3, v51
	v_fmac_f32_e32 v7, v1, v51
	v_fmac_f32_e32 v6, v2, v49
	v_fmac_f32_e32 v7, v3, v49
	v_fmac_f32_e32 v7, v2, v70
	v_cvt_pk_bf16_f32 v6, v6, v7
	ds_write_b16 v187, v6 offset:6336
	ds_write_b16_d16_hi v187, v6 offset:6480
	v_fma_f32 v6, v0, v51, v4
	v_fmac_f32_e32 v6, v1, v49
	v_fma_f32 v7, v0, v49, v4
	v_fmac_f32_e32 v6, v3, v70
	v_fmac_f32_e32 v7, v1, v70
	v_fmac_f32_e32 v6, v2, v68
	v_fmac_f32_e32 v7, v3, v68
	v_fmac_f32_e32 v7, v2, v65
	v_cvt_pk_bf16_f32 v6, v6, v7
	ds_write_b16 v187, v6 offset:6624
	ds_write_b16_d16_hi v187, v6 offset:6768
	v_fma_f32 v6, v0, v70, v4
	v_fmac_f32_e32 v6, v1, v68
	v_fma_f32 v7, v0, v68, v4
	v_fmac_f32_e32 v6, v3, v65
	v_fmac_f32_e32 v7, v1, v65
	v_fmac_f32_e32 v6, v2, v64
	v_fmac_f32_e32 v7, v3, v64
	v_fmac_f32_e32 v7, v2, v63
	v_cvt_pk_bf16_f32 v6, v6, v7
	ds_write_b16 v187, v6 offset:6912
	ds_write_b16_d16_hi v187, v6 offset:7056
; #define LAS __attribute__((address_space(3)))
; #define GAS __attribute__((address_space(1)))
; __device__ __forceinline__ unsigned cvt_pk_bf16(float lo, float hi) { unsigned r; asm volatile("v_cvt_pk_bf16_f32 %0, %1, %2" : "=v"(r) : "v"(lo), "v"(hi)); return r; }
; __device__ __forceinline__ int lru_pass1(const Params& P, int l, LAS unsigned char* lds, unsigned* qw) {
;     ...
;             for (int p = 0; p < 64; p += 2) { const float xc0 = cb + w0 * xv[p] + w1 * xv[p + 1] + w2 * xv[p + 2] + w3 * xv[p + 3], xc1 = cb + w0 * xv[p + 1] + w1 * xv[p + 2] + w2 * xv[p + 3] + w3 * xv[p + 4];
;                 const unsigned pk = cvt_pk_bf16(xc0, xc1); xcS[p * 72 + lane] = (unsigned short)pk; xcS[(p + 1) * 72 + lane] = (unsigned short)(pk >> 16); }
;         }
;         asm volatile("s_waitcnt lgkmcnt(0)" ::: "memory");
;         bf16x8 Af[4][2];
; #pragma unroll
;         for (int mt = 0; mt < 4; ++mt)
; #pragma unroll
;             for (int kk = 0; kk < 2; ++kk) { const int row = 16 * (fr >> 2) + 4 * mt + (fr & 3); Af[mt][kk] = *(const LAS bf16x8*)(xcS + row * 72 + kk * 32 + 8 * fq); }
; #pragma unroll 1
;         for (int jt = 0; jt < 4; ++jt) { const int cl = 16 * jt + fr, c = h * 64 + cl;
;             f32x4 acc[4][4];
; #pragma unroll
;             for (int mt = 0; mt < 4; ++mt)
; #pragma unroll
;                 for (int dt = 0; dt < 4; ++dt) acc[mt][dt] = (f32x4){0.f, 0.f, 0.f, 0.f};
;             bf16x8 Bfr[4][2];
; #pragma unroll
;             for (int dt = 0; dt < 4; ++dt)
; #pragma unroll
;                 for (int kk = 0; kk < 2; ++kk) Bfr[dt][kk] = *(const GAS bf16x8*)(WGT + ((size_t)((dt * 8 + h) * 64 + cl)) * 64 + kk * 32 + 8 * fq);
	v_fma_f32 v6, v0, v65, v4
	v_fmac_f32_e32 v6, v1, v64
	v_fma_f32 v7, v0, v64, v4
	v_fmac_f32_e32 v6, v3, v63
	v_fmac_f32_e32 v7, v1, v63
	v_fmac_f32_e32 v6, v2, v61
	v_fmac_f32_e32 v7, v3, v61
	v_fmac_f32_e32 v7, v2, v59
	v_cvt_pk_bf16_f32 v6, v6, v7
	ds_write_b16 v187, v6 offset:7200
	ds_write_b16_d16_hi v187, v6 offset:7344
	v_fma_f32 v6, v0, v63, v4
	v_fmac_f32_e32 v6, v1, v61
	v_fma_f32 v7, v0, v61, v4
	v_fmac_f32_e32 v6, v3, v59
	v_fmac_f32_e32 v7, v1, v59
	v_fmac_f32_e32 v6, v2, v57
	v_fmac_f32_e32 v7, v3, v57
	v_fmac_f32_e32 v7, v2, v77
	v_cvt_pk_bf16_f32 v6, v6, v7
	ds_write_b16 v187, v6 offset:7488
	ds_write_b16_d16_hi v187, v6 offset:7632
	v_fma_f32 v6, v0, v59, v4
	v_fmac_f32_e32 v6, v1, v57
	v_fma_f32 v7, v0, v57, v4
	v_fmac_f32_e32 v6, v3, v77
	v_fmac_f32_e32 v7, v1, v77
	v_fmac_f32_e32 v6, v2, v76
	v_fmac_f32_e32 v7, v3, v76
	v_or_b32_e32 v66, 60, v37
	v_fmac_f32_e32 v7, v2, v73
	v_cvt_pk_bf16_f32 v6, v6, v7
	v_cmp_lt_u32_e32 vcc, v66, v5
	ds_write_b16 v187, v6 offset:7776
	ds_write_b16_d16_hi v187, v6 offset:7920
	v_fma_f32 v6, v0, v77, v4
	v_cndmask_b32_e64 v66, 0, 1.0, vcc
	v_fmac_f32_e32 v6, v1, v76
	v_fma_f32 v7, v0, v76, v4
	v_mul_f32_e32 v66, v66, v67
	v_or_b32_e32 v67, 61, v37
	v_fmac_f32_e32 v6, v3, v73
	v_fmac_f32_e32 v7, v1, v73
	v_cmp_lt_u32_e32 vcc, v67, v5
	v_fmac_f32_e32 v6, v2, v72
	v_fmac_f32_e32 v7, v3, v72
	v_cndmask_b32_e64 v67, 0, 1.0, vcc
	v_fmac_f32_e32 v7, v2, v71
	v_cvt_pk_bf16_f32 v6, v6, v7
	v_mul_f32_e32 v67, v67, v74
	v_or_b32_e32 v74, 62, v37
	ds_write_b16 v187, v6 offset:8064
	ds_write_b16_d16_hi v187, v6 offset:8208
	v_fma_f32 v6, v0, v73, v4
	v_cmp_lt_u32_e32 vcc, v74, v5
	v_fmac_f32_e32 v6, v1, v72
	v_fma_f32 v7, v0, v72, v4
	s_waitcnt lgkmcnt(14)
	v_lshlrev_b32_e32 v75, 16, v75
	v_cndmask_b32_e64 v74, 0, 1.0, vcc
	v_fmac_f32_e32 v6, v3, v71
	v_fmac_f32_e32 v7, v1, v71
	v_mul_f32_e32 v74, v74, v75
	v_or_b32_e32 v75, 63, v37
	v_fmac_f32_e32 v6, v2, v69
	v_fmac_f32_e32 v7, v3, v69
	v_cmp_lt_u32_e32 vcc, v75, v5
	v_fmac_f32_e32 v7, v2, v66
	v_cvt_pk_bf16_f32 v6, v6, v7
	v_lshlrev_b32_e32 v78, 16, v78
	v_cndmask_b32_e64 v75, 0, 1.0, vcc
	ds_write_b16 v187, v6 offset:8352
	ds_write_b16_d16_hi v187, v6 offset:8496
	v_fma_f32 v6, v0, v71, v4
	v_mul_f32_e32 v75, v75, v78
	v_add_u32_e32 v78, 64, v37
	v_fmac_f32_e32 v6, v1, v69
	v_fma_f32 v7, v0, v69, v4
	v_ashrrev_i32_e32 v37, 31, v36
	v_fmac_f32_e32 v6, v3, v66
	v_fmac_f32_e32 v7, v1, v66
	v_lshlrev_b64 v[104:105], 10, v[36:37]
	v_fmac_f32_e32 v6, v2, v67
	v_fmac_f32_e32 v7, v3, v67
	v_lshl_add_u64 v[106:107], v[104:105], 0, s[0:1]
	s_mov_b64 s[0:1], 0xc00
	v_fmac_f32_e32 v7, v2, v74
	v_cvt_pk_bf16_f32 v6, v6, v7
	v_lshl_add_u64 v[110:111], v[104:105], 0, s[0:1]
	s_mov_b64 s[0:1], 0x1000
	v_cmp_lt_u32_e32 vcc, v78, v5
	ds_write_b16 v187, v6 offset:8640
	ds_write_b16_d16_hi v187, v6 offset:8784
	v_fma_f32 v6, v0, v66, v4
	v_fmac_f32_e32 v4, v0, v67
	v_lshl_add_u64 v[112:113], v[104:105], 0, s[0:1]
	s_mov_b64 s[0:1], 0x1400
	v_lshlrev_b32_e32 v79, 16, v79
	v_cndmask_b32_e64 v5, 0, 1.0, vcc
	v_fmac_f32_e32 v6, v1, v67
	v_fmac_f32_e32 v4, v1, v74
	v_lshl_add_u64 v[114:115], v[104:105], 0, s[0:1]
	s_mov_b64 s[0:1], 0x1800
	v_mul_f32_e32 v5, v5, v79
	v_fmac_f32_e32 v6, v3, v74
	v_fmac_f32_e32 v4, v3, v75
	v_lshl_add_u64 v[116:117], v[104:105], 0, s[0:1]
	s_mov_b64 s[0:1], 0x1c00
	v_fmac_f32_e32 v6, v2, v75
	v_fmac_f32_e32 v4, v2, v5
	v_cvt_pk_bf16_f32 v0, v6, v4
	v_lshl_add_u64 v[118:119], v[104:105], 0, s[0:1]
	s_mov_b64 s[0:1], 0x2000
	ds_write_b16 v187, v0 offset:8928
	ds_write_b16_d16_hi v187, v0 offset:9072
	v_lshl_add_u64 v[120:121], v[104:105], 0, s[0:1]
	s_mov_b64 s[0:1], 0x2400
	s_waitcnt lgkmcnt(0)
	v_lshl_add_u64 v[122:123], v[104:105], 0, s[0:1]
	s_mov_b64 s[0:1], 0x2800
	ds_read_b128 v[0:3], v211
	ds_read_b128 v[4:7], v211 offset:64
	ds_read_b128 v[8:11], v211 offset:576
	ds_read_b128 v[12:15], v211 offset:640
	ds_read_b128 v[16:19], v211 offset:1152
	ds_read_b128 v[20:23], v211 offset:1216
	ds_read_b128 v[24:27], v211 offset:1728
	ds_read_b128 v[28:31], v211 offset:1792
	v_lshl_add_u64 v[124:125], v[104:105], 0, s[0:1]
	s_mov_b64 s[0:1], 0x2c00
	v_lshl_add_u64 v[126:127], v[104:105], 0, s[0:1]
	s_mov_b64 s[0:1], 0x3000
	v_lshl_add_u64 v[138:139], v[104:105], 0, s[0:1]
	s_mov_b64 s[0:1], 0x3400
	v_lshl_add_u64 v[140:141], v[104:105], 0, s[0:1]
	s_mov_b64 s[0:1], 0x3800
	v_lshl_add_u64 v[142:143], v[104:105], 0, s[0:1]
	s_mov_b64 s[0:1], 0x3c00
	v_lshl_add_u64 v[144:145], v[104:105], 0, s[0:1]
	s_mov_b64 s[0:1], 0x123e2000
	v_lshl_add_u64 v[146:147], v[34:35], 0, s[0:1]
	v_lshl_or_b32 v34, v32, 13, v212
	v_readlane_b32 s0, v253, 38
	v_lshl_add_u64 v[148:149], v[100:101], 0, v[34:35]
	v_add_lshl_u32 v34, v99, v33, 2
	v_readlane_b32 s1, v253, 39
	v_add_u32_e32 v32, v185, v33
	v_lshl_add_u64 v[108:109], v[104:105], 0, s[64:65]
	v_lshl_add_u64 v[150:151], s[0:1], 0, v[34:35]
	v_add_u32_e32 v34, v209, v33
	v_lshl_add_u64 v[152:153], v[34:35], 2, v[134:135]
	v_add_u32_e32 v34, v210, v33
	v_lshl_add_u64 v[154:155], v[34:35], 2, s[0:1]
	v_lshl_or_b32 v102, v32, 2, v102
	v_lshl_add_u64 v[52:53], s[92:93], 0, v[148:149]
	v_add_co_u32_e32 v52, vcc, 0x4e00000, v52
	s_nop 1
	v_addc_co_u32_e32 v53, vcc, 0, v53, vcc
	global_load_dwordx4 v[224:227], v[52:53], off
	global_load_dwordx4 v[228:231], v[52:53], off offset:64
	v_add_co_u32_e32 v52, vcc, 0x10000, v52
	s_nop 1
	v_addc_co_u32_e32 v53, vcc, 0, v53, vcc
	global_load_dwordx4 v[232:235], v[52:53], off
	global_load_dwordx4 v[236:239], v[52:53], off offset:64
	v_add_co_u32_e32 v52, vcc, 0x10000, v52
	s_nop 1
	v_addc_co_u32_e32 v53, vcc, 0, v53, vcc
	global_load_dwordx4 v[240:243], v[52:53], off
	global_load_dwordx4 v[244:247], v[52:53], off offset:64
	s_branch .LBB0_557

; #define GAS __attribute__((address_space(1)))
; __device__ __forceinline__ int lru_pass1(const Params& P, int l, LAS unsigned char* lds, unsigned* qw) {
;     ...
;         for (int jt = 0; jt < 4; ++jt) { const int cl = 16 * jt + fr, c = h * 64 + cl;
;             f32x4 acc[4][4];
; #pragma unroll
;             for (int mt = 0; mt < 4; ++mt)
; #pragma unroll
;                 for (int dt = 0; dt < 4; ++dt) acc[mt][dt] = (f32x4){0.f, 0.f, 0.f, 0.f};
;             bf16x8 Bfr[4][2];
; #pragma unroll
;             for (int dt = 0; dt < 4; ++dt)
; #pragma unroll
;                 for (int kk = 0; kk < 2; ++kk) Bfr[dt][kk] = *(const GAS bf16x8*)(WGT + ((size_t)((dt * 8 + h) * 64 + cl)) * 64 + kk * 32 + 8 * fq);
;             __builtin_amdgcn_sched_barrier(0);
; #pragma unroll
;             for (int dt = 0; dt < 4; ++dt)
; #pragma unroll
;                 for (int kk = 0; kk < 2; ++kk) {
; #pragma unroll
;                     for (int mt = 0; mt < 4; ++mt) acc[mt][dt] = __builtin_amdgcn_mfma_f32_16x16x32_bf16(Af[mt][kk], Bfr[dt][kk], acc[mt][dt], 0, 0, 0); }
;             u32x2 abw[16];
; #pragma unroll
;             for (int d = 0; d < 2; ++d) {
;                 const float bgr = P.lru_bg[((l * 2 + d) * 2 + 0) * 512 + c], bgi = P.lru_bg[((l * 2 + d) * 2 + 1) * 512 + c];
;                 const float sp8 = SP8[(l * 2 + d) * 512 + c];
; #pragma unroll
;                 for (int mt = 0; mt < 4; ++mt)
; #pragma unroll
;                     for (int ip = 0; ip < 2; ++ip) { const int p = 16 * fq + 4 * mt + 2 * ip;
;                         const f32x2 xcv = (f32x2){bf2f(xcS[p * 72 + cl]), bf2f(xcS[(p + 1) * 72 + cl])};
;                         const f32x2 tr = ((f32x2){acc[mt][2 * d][2 * ip], acc[mt][2 * d][2 * ip + 1]} + bgr) * (-1.4426950408889634f);
;                         const f32x2 ti = ((f32x2){acc[mt][2 * d + 1][2 * ip], acc[mt][2 * d + 1][2 * ip + 1]} + bgi) * (-1.4426950408889634f);
;                         const f32x2 dr = (f32x2){__builtin_amdgcn_exp2f(tr.x), __builtin_amdgcn_exp2f(tr.y)} + 1.0f, di = (f32x2){__builtin_amdgcn_exp2f(ti.x), __builtin_amdgcn_exp2f(ti.y)} + 1.0f;
;                         const f32x2 r = (f32x2){__builtin_amdgcn_rcpf(dr.x), __builtin_amdgcn_rcpf(dr.y)}, ig = (f32x2){__builtin_amdgcn_rcpf(di.x), __builtin_amdgcn_rcpf(di.y)};
;                         const f32x2 la = r * (-sp8), x2 = la + la;
.LBB0_557:
	v_lshl_add_u64 v[54:55], v[154:155], 0, s[50:51]
	global_load_dword v218, v[54:55], off offset:-2048
	global_load_dword v219, v[54:55], off
	v_lshl_add_u64 v[54:55], s[92:93], 0, v[152:153]
	global_load_dword v220, v[54:55], off
	v_lshl_add_u64 v[54:55], v[150:151], 0, s[50:51]
	global_load_dword v221, v[54:55], off offset:-2048
	global_load_dword v222, v[54:55], off
	v_lshl_add_u64 v[54:55], s[92:93], 0, v[146:147]
	global_load_dword v223, v[54:55], off
	v_lshl_add_u64 v[52:53], s[92:93], 0, v[148:149]
	v_add_co_u32_e32 v52, vcc, 0x4e30000, v52
	s_nop 1
	v_addc_co_u32_e32 v53, vcc, 0, v53, vcc
	global_load_dwordx4 v[158:161], v[52:53], off
	global_load_dwordx4 v[162:165], v[52:53], off offset:64
	s_waitcnt vmcnt(8)
	v_mov_b32_e32 v32, v224
	v_mov_b32_e32 v33, v225
	v_mov_b32_e32 v34, v226
	v_mov_b32_e32 v35, v227
	v_mov_b32_e32 v36, v228
	v_mov_b32_e32 v37, v229
	v_mov_b32_e32 v38, v230
	v_mov_b32_e32 v39, v231
	v_mov_b32_e32 v40, v232
	v_mov_b32_e32 v41, v233
	v_mov_b32_e32 v42, v234
	v_mov_b32_e32 v43, v235
	v_mov_b32_e32 v44, v236
	v_mov_b32_e32 v45, v237
	v_mov_b32_e32 v46, v238
	v_mov_b32_e32 v47, v239
	v_mov_b32_e32 v48, v240
	v_mov_b32_e32 v49, v241
	v_mov_b32_e32 v50, v242
	v_mov_b32_e32 v51, v243
	v_mov_b32_e32 v56, v244
	v_mov_b32_e32 v57, v245
	v_mov_b32_e32 v58, v246
	v_mov_b32_e32 v59, v247
	s_nop 1
	s_waitcnt lgkmcnt(7)
	v_mfma_f32_16x16x32_bf16 v[52:55], v[0:3], v[32:35], 0
	s_waitcnt lgkmcnt(5)
	v_mfma_f32_16x16x32_bf16 v[60:63], v[8:11], v[32:35], 0
	s_waitcnt lgkmcnt(3)
	v_mfma_f32_16x16x32_bf16 v[64:67], v[16:19], v[32:35], 0
	s_waitcnt lgkmcnt(1)
	v_mfma_f32_16x16x32_bf16 v[32:35], v[24:27], v[32:35], 0
	v_mfma_f32_16x16x32_bf16 v[92:95], v[4:7], v[36:39], v[52:55]
	v_mfma_f32_16x16x32_bf16 v[84:87], v[12:15], v[36:39], v[60:63]
	v_mfma_f32_16x16x32_bf16 v[76:79], v[20:23], v[36:39], v[64:67]
	s_waitcnt lgkmcnt(0)
	v_mfma_f32_16x16x32_bf16 v[68:71], v[28:31], v[36:39], v[32:35]
	v_mfma_f32_16x16x32_bf16 v[32:35], v[0:3], v[40:43], 0
	v_mfma_f32_16x16x32_bf16 v[36:39], v[8:11], v[40:43], 0
	v_mfma_f32_16x16x32_bf16 v[52:55], v[16:19], v[40:43], 0
	v_mfma_f32_16x16x32_bf16 v[40:43], v[24:27], v[40:43], 0
	v_mfma_f32_16x16x32_bf16 v[88:91], v[4:7], v[44:47], v[32:35]
	v_mfma_f32_16x16x32_bf16 v[64:67], v[28:31], v[44:47], v[40:43]
	v_mfma_f32_16x16x32_bf16 v[32:35], v[0:3], v[48:51], 0
	v_mfma_f32_16x16x32_bf16 v[40:43], v[16:19], v[48:51], 0
	v_mfma_f32_16x16x32_bf16 v[80:83], v[12:15], v[44:47], v[36:39]
	v_mfma_f32_16x16x32_bf16 v[72:75], v[20:23], v[44:47], v[52:55]
	v_mfma_f32_16x16x32_bf16 v[36:39], v[8:11], v[48:51], 0
	v_mfma_f32_16x16x32_bf16 v[48:51], v[24:27], v[48:51], 0
	v_mfma_f32_16x16x32_bf16 v[60:63], v[4:7], v[56:59], v[32:35]
	v_mfma_f32_16x16x32_bf16 v[44:47], v[20:23], v[56:59], v[40:43]
	s_waitcnt vmcnt(1)
	v_mfma_f32_16x16x32_bf16 v[32:35], v[0:3], v[158:161], 0
	v_mfma_f32_16x16x32_bf16 v[40:43], v[8:11], v[158:161], 0
	v_mfma_f32_16x16x32_bf16 v[214:217], v[16:19], v[158:161], 0
	v_mfma_f32_16x16x32_bf16 v[158:161], v[24:27], v[158:161], 0
	v_mfma_f32_16x16x32_bf16 v[52:55], v[12:15], v[56:59], v[36:39]
	v_mfma_f32_16x16x32_bf16 v[36:39], v[28:31], v[56:59], v[48:51]
	s_waitcnt vmcnt(0)
	v_mfma_f32_16x16x32_bf16 v[56:59], v[4:7], v[162:165], v[32:35]
	v_mfma_f32_16x16x32_bf16 v[32:35], v[28:31], v[162:165], v[158:161]
	s_nop 2
	v_lshl_add_u64 v[158:159], v[154:155], 0, s[50:51]
	v_mov_b32_e32 v160, v218
	s_nop 0
	v_mov_b32_e32 v158, v219
	v_mfma_f32_16x16x32_bf16 v[48:51], v[12:15], v[162:165], v[40:43]
	s_waitcnt vmcnt(1)
	v_pk_add_f32 v[92:93], v[92:93], v[160:161] op_sel_hi:[1,0]
	v_mfma_f32_16x16x32_bf16 v[40:43], v[20:23], v[162:165], v[214:217]
	v_lshl_add_u64 v[162:163], s[92:93], 0, v[152:153]
	v_mov_b32_e32 v128, v220
	v_pk_mul_f32 v[92:93], v[92:93], s[18:19] op_sel_hi:[1,0]
	ds_read_u16 v159, v213
	ds_read_u16 v166, v213 offset:144
	v_exp_f32_e32 v92, v92
	v_exp_f32_e32 v93, v93
	s_nop 0
	v_pk_add_f32 v[92:93], v[92:93], 1.0 op_sel_hi:[1,0]
	s_nop 0
	v_rcp_f32_e32 v92, v92
	v_rcp_f32_e32 v93, v93
	s_waitcnt vmcnt(0)
	v_lshl_add_u64 v[162:163], s[92:93], 0, v[148:149]
	v_lshl_add_u64 v[162:163], v[162:163], 0, s[64:65]
	v_add_co_u32_e32 v162, vcc, 0x4e00000, v162
	s_nop 1
	v_addc_co_u32_e32 v163, vcc, 0, v163, vcc
	global_load_dwordx4 v[224:227], v[162:163], off
	global_load_dwordx4 v[228:231], v[162:163], off offset:64
	v_add_co_u32_e32 v162, vcc, 0x10000, v162
	s_nop 1
	v_addc_co_u32_e32 v163, vcc, 0, v163, vcc
	global_load_dwordx4 v[232:235], v[162:163], off
	global_load_dwordx4 v[236:239], v[162:163], off offset:64
	v_add_co_u32_e32 v162, vcc, 0x10000, v162
	s_nop 1
	v_addc_co_u32_e32 v163, vcc, 0, v163, vcc
	global_load_dwordx4 v[240:243], v[162:163], off
	global_load_dwordx4 v[244:247], v[162:163], off offset:64
	v_pk_mul_f32 v[92:93], v[128:129], v[92:93] op_sel_hi:[0,1] neg_lo:[1,0] neg_hi:[1,0]
	v_pk_add_f32 v[162:163], v[92:93], v[92:93]
	s_nop 0
	v_pk_fma_f32 v[164:165], v[162:163], s[20:21], v[136:137] op_sel_hi:[1,0,0]
	v_cmp_gt_f32_e64 s[46:47], s33, v162
	v_pk_fma_f32 v[164:165], v[162:163], v[164:165], s[22:23] op_sel_hi:[1,1,0]
	v_cmp_gt_f32_e64 s[44:45], s33, v163
	v_pk_fma_f32 v[164:165], v[162:163], v[164:165], 0.5 op_sel_hi:[1,1,0]
	s_or_b64 vcc, s[46:47], s[44:45]
	v_pk_fma_f32 v[164:165], v[162:163], v[164:165], 1.0 op_sel_hi:[1,1,0]
	s_nop 0
	v_pk_mul_f32 v[164:165], v[162:163], v[164:165] neg_lo:[0,1] neg_hi:[0,1]
	s_cbranch_vccnz .LBB0_577
